# plus batched residual-tile loads in the fused rmsnorm GEMM epilogues (S4/S7): 11 serialized load-wait-LDSwrite triples become two load batches
# speedup vs baseline: 1.0057x; 1.0057x over previous
; #define PG8_LAS __attribute__((address_space(3)))
;     __device__ __forceinline__ void fused(f32x4 (&acc)[2][2][4][2], const Unit& u, int wr, int wc, int fr, int fq, PG8_LAS unsigned char* lds, int wid, int lane) const {
;         typedef unsigned u32x2v __attribute__((ext_vector_type(2)));
;         constexpr int ldc = 2048; constexpr float inv_n = 1.0f / 2048.0f, eps = 1e-6f;
;         PG8_LAS f32x4* P = (PG8_LAS f32x4*)(lds + 131072);
;         PG8_LAS float* S = (PG8_LAS float*)(lds + 131072 + 16384);
;         const int col0 = u.pn * BM + wc * 32 + 8 * fq;
;         f32x4 gv[2][2];
; #pragma unroll
;         for (int bj = 0; bj < 2; ++bj)
; #pragma unroll
;             for (int n = 0; n < 2; ++n) gv[bj][n] = *(const f32x4*)(g1 + col0 + bj * HALF + n * 4);
;         PG8_LAS u32x4* XL = (PG8_LAS u32x4*)lds + (wid * 64 + lane);
; #pragma unroll
;         for (int ai = 0; ai < 2; ++ai)
; #pragma unroll
;             for (int m = 0; m < 4; ++m) { const size_t off = (size_t)(u.pm * BM + ai * HALF + wr * 64 + m * 16 + fr) * ldc + col0;
; #pragma unroll
;                 for (int bj = 0; bj < 2; ++bj) XL[((ai * 4 + m) * 2 + bj) * 512] = *(const u32x4*)(base_b + off + bj * HALF); }
.LBB0_831:
	v_readlane_b32 s0, v251, 17
	v_readlane_b32 s1, v251, 18
	v_readlane_b32 s2, v251, 19
	v_readlane_b32 s4, v251, 21
	v_readlane_b32 s0, v255, 21
	v_readlane_b32 s3, v251, 20
	v_readlane_b32 s5, v251, 22
	v_readlane_b32 s1, v255, 22
	s_add_u32 s2, s4, s0
	v_readlane_b32 s10, v251, 27
	s_addc_u32 s3, s5, s1
	s_lshl_b32 s0, s26, 5
	s_lshl_b32 s1, s25, 8
	v_lshrrev_b32_e32 v0, 1, v154
	s_or_b32 s0, s1, s0
	s_lshl_b32 s10, s24, 8
	v_and_or_b32 v176, v0, 24, s0
	s_add_i32 s0, s10, s20
	v_or_b32_e32 v164, s0, v178
	v_or_b32_e32 v158, 16, v164
	v_readlane_b32 s0, v251, 63
	v_ashrrev_i32_e32 v159, 31, v158
	v_ashrrev_i32_e32 v177, 31, v176
	v_readlane_b32 s1, v252, 0
	v_lshlrev_b64 v[158:159], 12, v[158:159]
	v_lshlrev_b64 v[166:167], 1, v[176:177]
	v_lshl_add_u64 v[158:159], s[0:1], 0, v[158:159]
	v_lshl_add_u64 v[134:135], v[176:177], 2, s[2:3]
	v_lshl_add_u64 v[172:173], v[158:159], 0, v[166:167]
	s_barrier
	global_load_dwordx4 v[138:141], v[134:135], off offset:16
	global_load_dwordx4 v[142:145], v[134:135], off
	global_load_dwordx4 v[130:133], v[134:135], off offset:528
	s_nop 0
	global_load_dwordx4 v[134:137], v[134:135], off offset:512
	v_and_b32_e32 v156, 63, v154
	global_load_dwordx4 v[158:161], v[172:173], off
	v_lshl_add_u32 v207, v156, 4, s30
	v_add_u32_e32 v206, 0x10000, v207
	v_add_u32_e32 v205, 0x12000, v207
	v_add_u32_e32 v204, 0x14000, v207
	v_add_u32_e32 v203, 0x16000, v207
	v_add_u32_e32 v202, 0x18000, v207
	v_add_u32_e32 v201, 0x1a000, v207
	v_ashrrev_i32_e32 v165, 31, v164
	v_lshlrev_b64 v[146:147], 12, v[164:165]
	v_lshl_add_u64 v[146:147], s[0:1], 0, v[146:147]
	v_lshl_add_u64 v[146:147], v[146:147], 0, v[166:167]
	global_load_dwordx4 v[150:153], v[146:147], off
	v_add_u32_e32 v0, 0x1c000, v207
	v_add_u32_e32 v200, 0x1e000, v207
	v_cmp_gt_u32_e32 vcc, 16, v156
	v_readlane_b32 s6, v251, 23
	v_readlane_b32 s7, v251, 24
	v_readlane_b32 s8, v251, 25
	v_readlane_b32 s9, v251, 26
	v_readlane_b32 s11, v251, 28
	v_readlane_b32 s12, v251, 29
	v_readlane_b32 s13, v251, 30
	v_readlane_b32 s14, v251, 31
	v_readlane_b32 s15, v251, 32
	s_waitcnt vmcnt(0)
	v_pk_mul_f32 v[218:219], v[116:117], v[132:133]
	v_pk_mul_f32 v[220:221], v[114:115], v[130:131]
	ds_write_b128 v207, v[158:161] offset:16384
	global_load_dwordx4 v[224:227], v[172:173], off offset:256
	v_or_b32_e32 v158, 32, v164
	v_ashrrev_i32_e32 v159, 31, v158
	v_lshlrev_b64 v[158:159], 12, v[158:159]
	v_lshl_add_u64 v[158:159], s[0:1], 0, v[158:159]
	v_lshl_add_u64 v[172:173], v[158:159], 0, v[166:167]
	global_load_dwordx4 v[228:231], v[172:173], off
	global_load_dwordx4 v[232:235], v[172:173], off offset:256
	v_or_b32_e32 v158, 48, v164
	v_ashrrev_i32_e32 v159, 31, v158
	v_lshlrev_b64 v[158:159], 12, v[158:159]
	v_lshl_add_u64 v[158:159], s[0:1], 0, v[158:159]
	v_lshl_add_u64 v[172:173], v[158:159], 0, v[166:167]
	global_load_dwordx4 v[236:239], v[172:173], off
	global_load_dwordx4 v[240:243], v[172:173], off offset:256
	v_add_u32_e32 v158, 0x80, v164
	v_ashrrev_i32_e32 v159, 31, v158
	v_lshlrev_b64 v[158:159], 12, v[158:159]
	v_lshl_add_u64 v[158:159], s[0:1], 0, v[158:159]
	v_lshl_add_u64 v[172:173], v[158:159], 0, v[166:167]
	global_load_dwordx4 v[244:247], v[172:173], off
	global_load_dwordx4 v[158:161], v[172:173], off offset:256
	s_waitcnt vmcnt(6)
	ds_write_b128 v207, v[224:227] offset:24576
	s_waitcnt vmcnt(5)
	ds_write_b128 v207, v[228:231] offset:32768
	s_waitcnt vmcnt(4)
	ds_write_b128 v207, v[232:235] offset:40960
	s_waitcnt vmcnt(3)
	ds_write_b128 v207, v[236:239] offset:49152
	s_waitcnt vmcnt(2)
	ds_write_b128 v207, v[240:243] offset:57344
	s_waitcnt vmcnt(1)
	ds_write_b128 v206, v[244:247]
	s_waitcnt vmcnt(0)
	ds_write_b128 v205, v[158:161]
	v_add_u32_e32 v158, 0x90, v164
	v_ashrrev_i32_e32 v159, 31, v158
	v_lshlrev_b64 v[158:159], 12, v[158:159]
	v_lshl_add_u64 v[158:159], s[0:1], 0, v[158:159]
	v_lshl_add_u64 v[172:173], v[158:159], 0, v[166:167]
	global_load_dwordx4 v[224:227], v[172:173], off
	global_load_dwordx4 v[228:231], v[172:173], off offset:256
	v_add_u32_e32 v158, 0xa0, v164
	v_ashrrev_i32_e32 v159, 31, v158
	v_lshlrev_b64 v[158:159], 12, v[158:159]
	v_lshl_add_u64 v[158:159], s[0:1], 0, v[158:159]
	v_lshl_add_u64 v[172:173], v[158:159], 0, v[166:167]
	global_load_dwordx4 v[232:235], v[172:173], off
	global_load_dwordx4 v[236:239], v[172:173], off offset:256
	v_add_u32_e32 v158, 0xb0, v164
	v_ashrrev_i32_e32 v159, 31, v158
	v_lshlrev_b64 v[158:159], 12, v[158:159]
	v_lshl_add_u64 v[158:159], s[0:1], 0, v[158:159]
	v_lshl_add_u64 v[164:165], v[158:159], 0, v[166:167]
	global_load_dwordx4 v[158:161], v[164:165], off
	v_pk_mul_f32 v[166:167], v[126:127], v[126:127]
	global_load_dwordx4 v[146:149], v[146:147], off offset:256
	ds_write_b128 v207, v[150:153]
	s_lshl_b32 s0, s26, 4
	s_add_i32 s4, s0, 0
	s_add_i32 s4, s4, 0x20000
	s_waitcnt vmcnt(1)
	ds_write_b128 v204, v[224:227]
	ds_write_b128 v203, v[228:231]
	ds_write_b128 v202, v[232:235]
	ds_write_b128 v201, v[236:239]
	ds_write_b128 v0, v[158:161]
	global_load_dwordx4 v[158:161], v[164:165], off offset:256
	v_pk_mul_f32 v[164:165], v[128:129], v[128:129]
	s_waitcnt vmcnt(1)
;     __device__ __forceinline__ void fused(f32x4 (&acc)[2][2][4][2], const Unit& u, int wr, int wc, int fr, int fq, PG8_LAS unsigned char* lds, int wid, int lane) const {
;     ...
;         for (int ai = 0; ai < 2; ++ai)
; #pragma unroll
;             for (int m = 0; m < 4; ++m) {
;                 float saa = 0.f, sxx = 0.f, sxag = 0.f, sgg = 0.f;
; #pragma unroll
;                 for (int bj = 0; bj < 2; ++bj) { const u32x4 w4 = XL[((ai * 4 + m) * 2 + bj) * 512];
; #pragma unroll
;                     for (int n = 0; n < 2; ++n) { const f32x4 a = acc[ai][bj][m][n]; const f32x4 ag = a * gv[bj][n]; const unsigned wx = n == 0 ? w4.x : w4.z, wy = n == 0 ? w4.y : w4.w;
;                         const f32x4 x = (f32x4){bflo(wx), bfhi(wx), bflo(wy), bfhi(wy)};
;                         saa += (a[0] * a[0] + a[1] * a[1]) + (a[2] * a[2] + a[3] * a[3]); sxx += (x[0] * x[0] + x[1] * x[1]) + (x[2] * x[2] + x[3] * x[3]);
;                         sxag += (x[0] * ag[0] + x[1] * ag[1]) + (x[2] * ag[2] + x[3] * ag[3]); sgg += (ag[0] * ag[0] + ag[1] * ag[1]) + (ag[2] * ag[2] + ag[3] * ag[3]); } }
;                 asm volatile("" : "+v"(saa), "+v"(sxx), "+v"(sxag), "+v"(sgg));
;                 saa += __shfl_xor(saa, 16); sxx += __shfl_xor(sxx, 16); sxag += __shfl_xor(sxag, 16); sgg += __shfl_xor(sgg, 16);
;                 saa += __shfl_xor(saa, 32); sxx += __shfl_xor(sxx, 32); sxag += __shfl_xor(sxag, 32); sgg += __shfl_xor(sgg, 32);
;                 if (fq == 0) P[(ai * HALF + wr * 64 + m * 16 + fr) * 4 + wc] = (f32x4){saa, sxx, sxag, sgg};
	v_lshlrev_b32_e32 v212, 16, v146
	v_pk_mov_b32 v[172:173], v[166:167], v[164:165] op_sel:[1,0]
	v_mov_b32_e32 v167, v165
	v_pk_add_f32 v[164:165], v[172:173], v[166:167]
	v_lshlrev_b32_e32 v166, 16, v150
	v_and_b32_e32 v173, 0xffff0000, v150
	v_and_b32_e32 v172, 16, v150
	v_mov_b32_e32 v167, v173
	v_mul_f32_e32 v150, v166, v166
	v_pk_fma_f32 v[174:175], v[166:167], v[166:167], v[150:151] op_sel_hi:[1,1,0]
	v_lshlrev_b32_e32 v150, 16, v151
	v_and_b32_e32 v151, 0xffff0000, v151
	v_mul_f32_e32 v162, v150, v150
	v_mov_b32_e32 v167, v151
	v_pk_fma_f32 v[180:181], v[150:151], v[150:151], v[162:163] op_sel_hi:[1,1,0]
	v_pk_mov_b32 v[172:173], v[172:173], v[150:151] op_sel:[1,0]
	ds_write_b128 v207, v[146:149] offset:8192
	v_and_b32_e32 v213, 0xffff0000, v146
	v_mul_f32_e32 v146, v212, v212
	v_pk_fma_f32 v[214:215], v[212:213], v[212:213], v[146:147] op_sel_hi:[1,1,0]
	v_lshlrev_b32_e32 v146, 16, v147
	v_and_b32_e32 v147, 0xffff0000, v147
	v_pk_add_f32 v[164:165], v[164:165], v[164:165] op_sel_hi:[0,1]
	v_lshlrev_b32_e32 v222, 16, v148
	v_lshlrev_b32_e32 v157, 16, v149
	v_and_b32_e32 v162, 0xffff0000, v149
	v_mul_f32_e32 v164, v117, v117
	v_mov_b32_e32 v223, v175
	v_mul_f32_e32 v214, v157, v157
	s_waitcnt vmcnt(0)
	ds_write_b128 v200, v[158:161]
	v_pk_mul_f32 v[158:159], v[128:129], v[144:145]
	v_pk_mul_f32 v[160:161], v[126:127], v[142:143]
	v_mov_b32_e32 v185, v159
	v_mov_b32_e32 v184, v160
	v_pk_mov_b32 v[182:183], v[160:161], v[158:159] op_sel:[1,0]
	v_pk_mul_f32 v[150:151], v[184:185], v[166:167]
	v_pk_mul_f32 v[158:159], v[158:159], v[158:159]
	v_pk_mul_f32 v[160:161], v[160:161], v[160:161]
	v_pk_fma_f32 v[150:151], v[182:183], v[172:173], v[150:151]
	v_pk_mov_b32 v[166:167], v[160:161], v[158:159] op_sel:[1,0]
	v_mov_b32_e32 v161, v159
	v_pk_mul_f32 v[172:173], v[124:125], v[124:125]
	v_pk_mul_f32 v[182:183], v[122:123], v[122:123]
	v_pk_add_f32 v[158:159], v[166:167], v[160:161]
	v_pk_mul_f32 v[160:161], v[124:125], v[140:141]
	v_pk_mul_f32 v[166:167], v[122:123], v[138:139]
	v_pk_mov_b32 v[184:185], v[182:183], v[172:173] op_sel:[1,0]
	v_mov_b32_e32 v183, v173
	v_add_f32_e32 v150, v150, v151
	v_pk_add_f32 v[172:173], v[184:185], v[182:183]
	v_lshlrev_b32_e32 v183, 16, v153
	v_lshlrev_b32_e32 v182, 16, v152
	v_and_b32_e32 v153, 0xffff0000, v153
	v_and_b32_e32 v152, 0xffff0000, v152
	v_mov_b32_e32 v210, v167
	v_mov_b32_e32 v211, v161
	v_add_f32_e32 v151, 0, v150
	v_pk_mul_f32 v[184:185], v[152:153], v[152:153]
	v_mov_b32_e32 v208, v166
	v_mov_b32_e32 v209, v160
	v_pk_mul_f32 v[152:153], v[210:211], v[152:153]
	v_pk_mul_f32 v[160:161], v[160:161], v[160:161]
	v_pk_mul_f32 v[166:167], v[166:167], v[166:167]
	v_mul_f32_e32 v150, v118, v118
	v_pk_fma_f32 v[184:185], v[182:183], v[182:183], v[184:185]
	v_pk_fma_f32 v[152:153], v[208:209], v[182:183], v[152:153]
	v_pk_mov_b32 v[182:183], v[166:167], v[160:161] op_sel:[1,0]
	v_mov_b32_e32 v167, v161
	v_pk_fma_f32 v[208:209], v[118:119], v[118:119], v[150:151] op_sel_hi:[1,1,0]
	v_mul_f32_e32 v150, v120, v120
	v_pk_add_f32 v[160:161], v[182:183], v[166:167]
	v_pk_mul_f32 v[182:183], v[118:119], v[134:135]
	v_pk_fma_f32 v[210:211], v[120:121], v[120:121], v[150:151] op_sel_hi:[1,1,0]
	v_mul_f32_e32 v150, v146, v146
	v_pk_mul_f32 v[166:167], v[120:121], v[136:137]
	v_pk_fma_f32 v[216:217], v[146:147], v[146:147], v[150:151] op_sel_hi:[1,1,0]
	v_mul_f32_e32 v150, v182, v212
	v_pk_fma_f32 v[212:213], v[182:183], v[212:213], v[150:151] op_sel_hi:[1,1,0]
	v_mul_f32_e32 v150, v166, v146
	v_pk_add_f32 v[172:173], v[172:173], v[172:173] op_sel_hi:[0,1]
	v_pk_fma_f32 v[146:147], v[166:167], v[146:147], v[150:151] op_sel_hi:[1,1,0]
	v_pk_add_f32 v[184:185], v[184:185], v[184:185] op_sel_hi:[0,1]
	v_pk_add_f32 v[152:153], v[152:153], v[152:153] op_sel_hi:[0,1]
	v_and_b32_e32 v146, 0xffff0000, v148
	v_mul_f32_e32 v208, v114, v114
	v_mul_f32_e32 v210, v115, v115
	v_mul_f32_e32 v172, v116, v116
	v_pk_add_f32 v[148:149], v[208:209], v[210:211]
	v_pk_add_f32 v[164:165], v[172:173], v[164:165]
	v_mul_f32_e32 v184, v146, v146
	v_mul_f32_e32 v152, v220, v222
	v_mul_f32_e32 v150, v221, v146
	v_mul_f32_e32 v212, v218, v157
	v_mul_f32_e32 v146, v219, v162
	v_pk_add_f32 v[148:149], v[148:149], v[164:165]
	v_mov_b32_e32 v164, v222
	v_mov_b32_e32 v165, v181
	v_pk_add_f32 v[150:151], v[152:153], v[150:151]
	v_pk_add_f32 v[146:147], v[212:213], v[146:147]
	v_pk_mul_f32 v[164:165], v[222:223], v[164:165]
	v_pk_add_f32 v[172:173], v[174:175], v[180:181]
	v_pk_add_f32 v[146:147], v[150:151], v[146:147]
	v_mul_f32_e32 v216, v162, v162
	v_mov_b32_e32 v165, v173
	v_add_f32_e32 v150, v146, v147
	v_mul_f32_e32 v151, v220, v220
	v_mul_f32_e32 v157, v221, v221
	v_pk_add_f32 v[146:147], v[158:159], v[158:159] op_sel:[0,1] op_sel_hi:[1,0]
	v_pk_add_f32 v[152:153], v[160:161], v[160:161] op_sel:[0,1] op_sel_hi:[1,0]
	v_pk_add_f32 v[164:165], v[164:165], v[184:185]
	v_pk_add_f32 v[172:173], v[214:215], v[216:217]
	v_mov_b32_e32 v147, v151
	v_mov_b32_e32 v153, v157
	v_pk_add_f32 v[164:165], v[164:165], v[172:173]
	v_pk_add_f32 v[146:147], v[146:147], v[152:153]
	v_mul_f32_e32 v152, v183, v183
	v_mul_f32_e32 v158, v167, v167
	v_add_f32_e32 v148, v148, v149
	v_add_f32_e32 v149, v164, v165
	v_mul_f32_e32 v162, v218, v218
	v_mul_f32_e32 v164, v219, v219
	v_pk_fma_f32 v[152:153], v[182:183], v[182:183], v[152:153] op_sel_hi:[1,1,0]
	v_pk_fma_f32 v[158:159], v[166:167], v[166:167], v[158:159] op_sel_hi:[1,1,0]
	v_mov_b32_e32 v153, v162
	v_mov_b32_e32 v159, v164
	v_pk_add_f32 v[152:153], v[152:153], v[158:159]
	s_nop 0
	v_pk_add_f32 v[146:147], v[146:147], v[152:153]
	s_nop 0
	v_add_f32_e32 v151, v146, v147
	ds_bpermute_b32 v146, v187, v148
	ds_bpermute_b32 v147, v187, v149
	s_waitcnt lgkmcnt(0)
	v_pk_add_f32 v[146:147], v[148:149], v[146:147]
	ds_bpermute_b32 v148, v187, v150
	ds_bpermute_b32 v149, v187, v151
	s_waitcnt lgkmcnt(0)
	v_pk_add_f32 v[150:151], v[150:151], v[148:149]
	ds_bpermute_b32 v148, v186, v146
	ds_bpermute_b32 v149, v186, v147
	ds_bpermute_b32 v152, v186, v150
	ds_bpermute_b32 v153, v186, v151
	s_and_saveexec_b64 s[0:1], vcc
	s_cbranch_execz .LBB0_833
	s_lshl_b32 s5, s23, 12
	s_add_i32 s5, s4, s5
	s_waitcnt lgkmcnt(0)
	v_pk_add_f32 v[150:151], v[150:151], v[152:153]
	v_pk_add_f32 v[148:149], v[146:147], v[148:149]
	v_add_u32_e32 v146, s5, v155
	ds_write_b128 v146, v[148:151]

; #define PG8_LAS __attribute__((address_space(3)))
;     __device__ __forceinline__ void fused(f32x4 (&acc)[2][2][4][2], const Unit& u, int wr, int wc, int fr, int fq, PG8_LAS unsigned char* lds, int wid, int lane) const {
;         typedef unsigned u32x2v __attribute__((ext_vector_type(2)));
;         constexpr int ldc = 2048; constexpr float inv_n = 1.0f / 2048.0f, eps = 1e-6f;
;         PG8_LAS f32x4* P = (PG8_LAS f32x4*)(lds + 131072);
;         PG8_LAS float* S = (PG8_LAS float*)(lds + 131072 + 16384);
;         const int col0 = u.pn * BM + wc * 32 + 8 * fq;
;         f32x4 gv[2][2];
; #pragma unroll
;         for (int bj = 0; bj < 2; ++bj)
; #pragma unroll
;             for (int n = 0; n < 2; ++n) gv[bj][n] = *(const f32x4*)(g1 + col0 + bj * HALF + n * 4);
;         PG8_LAS u32x4* XL = (PG8_LAS u32x4*)lds + (wid * 64 + lane);
; #pragma unroll
;         for (int ai = 0; ai < 2; ++ai)
; #pragma unroll
;             for (int m = 0; m < 4; ++m) { const size_t off = (size_t)(u.pm * BM + ai * HALF + wr * 64 + m * 16 + fr) * ldc + col0;
; #pragma unroll
;                 for (int bj = 0; bj < 2; ++bj) XL[((ai * 4 + m) * 2 + bj) * 512] = *(const u32x4*)(base_b + off + bj * HALF); }
.LBB0_1071:
	v_readlane_b32 s0, v251, 17
	v_readlane_b32 s1, v251, 18
	v_readlane_b32 s2, v251, 19
	v_readlane_b32 s8, v251, 25
	v_readlane_b32 s0, v255, 21
	v_readlane_b32 s3, v251, 20
	v_readlane_b32 s9, v251, 26
	v_readlane_b32 s1, v255, 22
	s_add_u32 s2, s8, s0
	v_readlane_b32 s10, v251, 27
	s_addc_u32 s3, s9, s1
	s_lshl_b32 s0, s22, 5
	s_lshl_b32 s1, s21, 8
	v_lshrrev_b32_e32 v0, 1, v154
	s_or_b32 s0, s1, s0
	s_lshl_b32 s10, s20, 8
	v_and_or_b32 v176, v0, 24, s0
	s_add_i32 s0, s10, s16
	v_or_b32_e32 v164, s0, v178
	v_or_b32_e32 v158, 16, v164
	v_readlane_b32 s0, v251, 63
	v_ashrrev_i32_e32 v159, 31, v158
	v_ashrrev_i32_e32 v177, 31, v176
	v_readlane_b32 s1, v252, 0
	v_lshlrev_b64 v[158:159], 12, v[158:159]
	v_lshlrev_b64 v[166:167], 1, v[176:177]
	v_lshl_add_u64 v[158:159], s[0:1], 0, v[158:159]
	v_lshl_add_u64 v[134:135], v[176:177], 2, s[2:3]
	v_lshl_add_u64 v[172:173], v[158:159], 0, v[166:167]
	s_barrier
	global_load_dwordx4 v[138:141], v[134:135], off offset:16
	global_load_dwordx4 v[142:145], v[134:135], off
	global_load_dwordx4 v[130:133], v[134:135], off offset:528
	s_nop 0
	global_load_dwordx4 v[134:137], v[134:135], off offset:512
	v_and_b32_e32 v156, 63, v154
	global_load_dwordx4 v[158:161], v[172:173], off
	v_lshl_add_u32 v207, v156, 4, s26
	v_add_u32_e32 v206, 0x10000, v207
	v_add_u32_e32 v205, 0x12000, v207
	v_add_u32_e32 v204, 0x14000, v207
	v_add_u32_e32 v203, 0x16000, v207
	v_add_u32_e32 v202, 0x18000, v207
	v_add_u32_e32 v201, 0x1a000, v207
	v_ashrrev_i32_e32 v165, 31, v164
	v_lshlrev_b64 v[146:147], 12, v[164:165]
	v_lshl_add_u64 v[146:147], s[0:1], 0, v[146:147]
	v_lshl_add_u64 v[146:147], v[146:147], 0, v[166:167]
	global_load_dwordx4 v[150:153], v[146:147], off
	v_add_u32_e32 v200, 0x1c000, v207
	v_add_u32_e32 v0, 0x1e000, v207
	v_readlane_b32 s4, v251, 21
	v_cmp_gt_u32_e32 vcc, 16, v156
	v_readlane_b32 s5, v251, 22
	v_readlane_b32 s6, v251, 23
	v_readlane_b32 s7, v251, 24
	v_readlane_b32 s11, v251, 28
	v_readlane_b32 s12, v251, 29
	v_readlane_b32 s13, v251, 30
	v_readlane_b32 s14, v251, 31
	v_readlane_b32 s15, v251, 32
	s_waitcnt vmcnt(0)
	v_pk_mul_f32 v[218:219], v[116:117], v[132:133]
	v_pk_mul_f32 v[220:221], v[114:115], v[130:131]
	ds_write_b128 v207, v[158:161] offset:16384
	global_load_dwordx4 v[224:227], v[172:173], off offset:256
	v_or_b32_e32 v158, 32, v164
	v_ashrrev_i32_e32 v159, 31, v158
	v_lshlrev_b64 v[158:159], 12, v[158:159]
	v_lshl_add_u64 v[158:159], s[0:1], 0, v[158:159]
	v_lshl_add_u64 v[172:173], v[158:159], 0, v[166:167]
	global_load_dwordx4 v[228:231], v[172:173], off
	global_load_dwordx4 v[232:235], v[172:173], off offset:256
	v_or_b32_e32 v158, 48, v164
	v_ashrrev_i32_e32 v159, 31, v158
	v_lshlrev_b64 v[158:159], 12, v[158:159]
	v_lshl_add_u64 v[158:159], s[0:1], 0, v[158:159]
	v_lshl_add_u64 v[172:173], v[158:159], 0, v[166:167]
	global_load_dwordx4 v[236:239], v[172:173], off
	global_load_dwordx4 v[240:243], v[172:173], off offset:256
	v_add_u32_e32 v158, 0x80, v164
	v_ashrrev_i32_e32 v159, 31, v158
	v_lshlrev_b64 v[158:159], 12, v[158:159]
	v_lshl_add_u64 v[158:159], s[0:1], 0, v[158:159]
	v_lshl_add_u64 v[172:173], v[158:159], 0, v[166:167]
	global_load_dwordx4 v[244:247], v[172:173], off
	global_load_dwordx4 v[158:161], v[172:173], off offset:256
	s_waitcnt vmcnt(6)
	ds_write_b128 v207, v[224:227] offset:24576
	s_waitcnt vmcnt(5)
	ds_write_b128 v207, v[228:231] offset:32768
	s_waitcnt vmcnt(4)
	ds_write_b128 v207, v[232:235] offset:40960
	s_waitcnt vmcnt(3)
	ds_write_b128 v207, v[236:239] offset:49152
	s_waitcnt vmcnt(2)
	ds_write_b128 v207, v[240:243] offset:57344
	s_waitcnt vmcnt(1)
	ds_write_b128 v206, v[244:247]
	s_waitcnt vmcnt(0)
	ds_write_b128 v205, v[158:161]
	v_add_u32_e32 v158, 0x90, v164
	v_ashrrev_i32_e32 v159, 31, v158
	v_lshlrev_b64 v[158:159], 12, v[158:159]
	v_lshl_add_u64 v[158:159], s[0:1], 0, v[158:159]
	v_lshl_add_u64 v[172:173], v[158:159], 0, v[166:167]
	global_load_dwordx4 v[224:227], v[172:173], off
	global_load_dwordx4 v[228:231], v[172:173], off offset:256
	v_add_u32_e32 v158, 0xa0, v164
	v_ashrrev_i32_e32 v159, 31, v158
	v_lshlrev_b64 v[158:159], 12, v[158:159]
	v_lshl_add_u64 v[158:159], s[0:1], 0, v[158:159]
	v_lshl_add_u64 v[172:173], v[158:159], 0, v[166:167]
	global_load_dwordx4 v[232:235], v[172:173], off
	global_load_dwordx4 v[236:239], v[172:173], off offset:256
	v_add_u32_e32 v158, 0xb0, v164
	v_ashrrev_i32_e32 v159, 31, v158
	v_lshlrev_b64 v[158:159], 12, v[158:159]
	v_lshl_add_u64 v[158:159], s[0:1], 0, v[158:159]
	v_lshl_add_u64 v[164:165], v[158:159], 0, v[166:167]
	global_load_dwordx4 v[158:161], v[164:165], off
	v_pk_mul_f32 v[166:167], v[126:127], v[126:127]
	global_load_dwordx4 v[146:149], v[146:147], off offset:256
	ds_write_b128 v207, v[150:153]
	s_lshl_b32 s0, s22, 4
	s_add_i32 s4, s0, 0
	s_add_i32 s4, s4, 0x20000
	s_waitcnt vmcnt(1)
	ds_write_b128 v204, v[224:227]
	ds_write_b128 v203, v[228:231]
	ds_write_b128 v202, v[232:235]
	ds_write_b128 v201, v[236:239]
	ds_write_b128 v200, v[158:161]
	global_load_dwordx4 v[158:161], v[164:165], off offset:256
	v_pk_mul_f32 v[164:165], v[128:129], v[128:129]
	s_waitcnt vmcnt(1)
;     __device__ __forceinline__ void fused(f32x4 (&acc)[2][2][4][2], const Unit& u, int wr, int wc, int fr, int fq, PG8_LAS unsigned char* lds, int wid, int lane) const {
;     ...
;         for (int ai = 0; ai < 2; ++ai)
; #pragma unroll
;             for (int m = 0; m < 4; ++m) {
;                 float saa = 0.f, sxx = 0.f, sxag = 0.f, sgg = 0.f;
; #pragma unroll
;                 for (int bj = 0; bj < 2; ++bj) { const u32x4 w4 = XL[((ai * 4 + m) * 2 + bj) * 512];
; #pragma unroll
;                     for (int n = 0; n < 2; ++n) { const f32x4 a = acc[ai][bj][m][n]; const f32x4 ag = a * gv[bj][n]; const unsigned wx = n == 0 ? w4.x : w4.z, wy = n == 0 ? w4.y : w4.w;
;                         const f32x4 x = (f32x4){bflo(wx), bfhi(wx), bflo(wy), bfhi(wy)};
;                         saa += (a[0] * a[0] + a[1] * a[1]) + (a[2] * a[2] + a[3] * a[3]); sxx += (x[0] * x[0] + x[1] * x[1]) + (x[2] * x[2] + x[3] * x[3]);
;                         sxag += (x[0] * ag[0] + x[1] * ag[1]) + (x[2] * ag[2] + x[3] * ag[3]); sgg += (ag[0] * ag[0] + ag[1] * ag[1]) + (ag[2] * ag[2] + ag[3] * ag[3]); } }
;                 asm volatile("" : "+v"(saa), "+v"(sxx), "+v"(sxag), "+v"(sgg));
;                 saa += __shfl_xor(saa, 16); sxx += __shfl_xor(sxx, 16); sxag += __shfl_xor(sxag, 16); sgg += __shfl_xor(sgg, 16);
;                 saa += __shfl_xor(saa, 32); sxx += __shfl_xor(sxx, 32); sxag += __shfl_xor(sxag, 32); sgg += __shfl_xor(sgg, 32);
;                 if (fq == 0) P[(ai * HALF + wr * 64 + m * 16 + fr) * 4 + wc] = (f32x4){saa, sxx, sxag, sgg};
	v_lshlrev_b32_e32 v212, 16, v146
	v_pk_mov_b32 v[172:173], v[166:167], v[164:165] op_sel:[1,0]
	v_mov_b32_e32 v167, v165
	v_pk_add_f32 v[164:165], v[172:173], v[166:167]
	v_lshlrev_b32_e32 v166, 16, v150
	v_and_b32_e32 v173, 0xffff0000, v150
	v_and_b32_e32 v172, 16, v150
	v_mov_b32_e32 v167, v173
	v_mul_f32_e32 v150, v166, v166
	v_pk_fma_f32 v[174:175], v[166:167], v[166:167], v[150:151] op_sel_hi:[1,1,0]
	v_lshlrev_b32_e32 v150, 16, v151
	v_and_b32_e32 v151, 0xffff0000, v151
	v_mul_f32_e32 v162, v150, v150
	v_mov_b32_e32 v167, v151
	v_pk_fma_f32 v[180:181], v[150:151], v[150:151], v[162:163] op_sel_hi:[1,1,0]
	v_pk_mov_b32 v[172:173], v[172:173], v[150:151] op_sel:[1,0]
	ds_write_b128 v207, v[146:149] offset:8192
	v_and_b32_e32 v213, 0xffff0000, v146
	v_mul_f32_e32 v146, v212, v212
	v_pk_fma_f32 v[214:215], v[212:213], v[212:213], v[146:147] op_sel_hi:[1,1,0]
	v_lshlrev_b32_e32 v146, 16, v147
	v_and_b32_e32 v147, 0xffff0000, v147
	v_pk_add_f32 v[164:165], v[164:165], v[164:165] op_sel_hi:[0,1]
	v_lshlrev_b32_e32 v222, 16, v148
	v_lshlrev_b32_e32 v157, 16, v149
	v_and_b32_e32 v162, 0xffff0000, v149
	v_mul_f32_e32 v164, v117, v117
	v_mov_b32_e32 v223, v175
	v_mul_f32_e32 v214, v157, v157
	s_waitcnt vmcnt(0)
	ds_write_b128 v0, v[158:161]
	v_pk_mul_f32 v[158:159], v[128:129], v[144:145]
	v_pk_mul_f32 v[160:161], v[126:127], v[142:143]
	v_mov_b32_e32 v185, v159
	v_mov_b32_e32 v184, v160
	v_pk_mov_b32 v[182:183], v[160:161], v[158:159] op_sel:[1,0]
	v_pk_mul_f32 v[150:151], v[184:185], v[166:167]
	v_pk_mul_f32 v[158:159], v[158:159], v[158:159]
	v_pk_mul_f32 v[160:161], v[160:161], v[160:161]
	v_pk_fma_f32 v[150:151], v[182:183], v[172:173], v[150:151]
	v_pk_mov_b32 v[166:167], v[160:161], v[158:159] op_sel:[1,0]
	v_mov_b32_e32 v161, v159
	v_pk_mul_f32 v[172:173], v[124:125], v[124:125]
	v_pk_mul_f32 v[182:183], v[122:123], v[122:123]
	v_pk_add_f32 v[158:159], v[166:167], v[160:161]
	v_pk_mul_f32 v[160:161], v[124:125], v[140:141]
	v_pk_mul_f32 v[166:167], v[122:123], v[138:139]
	v_pk_mov_b32 v[184:185], v[182:183], v[172:173] op_sel:[1,0]
	v_mov_b32_e32 v183, v173
	v_add_f32_e32 v150, v150, v151
	v_pk_add_f32 v[172:173], v[184:185], v[182:183]
	v_lshlrev_b32_e32 v183, 16, v153
	v_lshlrev_b32_e32 v182, 16, v152
	v_and_b32_e32 v153, 0xffff0000, v153
	v_and_b32_e32 v152, 0xffff0000, v152
	v_mov_b32_e32 v210, v167
	v_mov_b32_e32 v211, v161
	v_add_f32_e32 v151, 0, v150
	v_pk_mul_f32 v[184:185], v[152:153], v[152:153]
	v_mov_b32_e32 v208, v166
	v_mov_b32_e32 v209, v160
	v_pk_mul_f32 v[152:153], v[210:211], v[152:153]
	v_pk_mul_f32 v[160:161], v[160:161], v[160:161]
	v_pk_mul_f32 v[166:167], v[166:167], v[166:167]
	v_mul_f32_e32 v150, v118, v118
	v_pk_fma_f32 v[184:185], v[182:183], v[182:183], v[184:185]
	v_pk_fma_f32 v[152:153], v[208:209], v[182:183], v[152:153]
	v_pk_mov_b32 v[182:183], v[166:167], v[160:161] op_sel:[1,0]
	v_mov_b32_e32 v167, v161
	v_pk_fma_f32 v[208:209], v[118:119], v[118:119], v[150:151] op_sel_hi:[1,1,0]
	v_mul_f32_e32 v150, v120, v120
	v_pk_add_f32 v[160:161], v[182:183], v[166:167]
	v_pk_mul_f32 v[182:183], v[118:119], v[134:135]
	v_pk_fma_f32 v[210:211], v[120:121], v[120:121], v[150:151] op_sel_hi:[1,1,0]
	v_mul_f32_e32 v150, v146, v146
	v_pk_mul_f32 v[166:167], v[120:121], v[136:137]
	v_pk_fma_f32 v[216:217], v[146:147], v[146:147], v[150:151] op_sel_hi:[1,1,0]
	v_mul_f32_e32 v150, v182, v212
	v_pk_fma_f32 v[212:213], v[182:183], v[212:213], v[150:151] op_sel_hi:[1,1,0]
	v_mul_f32_e32 v150, v166, v146
	v_pk_add_f32 v[172:173], v[172:173], v[172:173] op_sel_hi:[0,1]
	v_pk_fma_f32 v[146:147], v[166:167], v[146:147], v[150:151] op_sel_hi:[1,1,0]
	v_pk_add_f32 v[184:185], v[184:185], v[184:185] op_sel_hi:[0,1]
	v_pk_add_f32 v[152:153], v[152:153], v[152:153] op_sel_hi:[0,1]
	v_and_b32_e32 v146, 0xffff0000, v148
	v_mul_f32_e32 v208, v114, v114
	v_mul_f32_e32 v210, v115, v115
	v_mul_f32_e32 v172, v116, v116
	v_pk_add_f32 v[148:149], v[208:209], v[210:211]
	v_pk_add_f32 v[164:165], v[172:173], v[164:165]
	v_mul_f32_e32 v184, v146, v146
	v_mul_f32_e32 v152, v220, v222
	v_mul_f32_e32 v150, v221, v146
	v_mul_f32_e32 v212, v218, v157
	v_mul_f32_e32 v146, v219, v162
	v_pk_add_f32 v[148:149], v[148:149], v[164:165]
	v_mov_b32_e32 v164, v222
	v_mov_b32_e32 v165, v181
	v_pk_add_f32 v[150:151], v[152:153], v[150:151]
	v_pk_add_f32 v[146:147], v[212:213], v[146:147]
	v_pk_mul_f32 v[164:165], v[222:223], v[164:165]
	v_pk_add_f32 v[172:173], v[174:175], v[180:181]
	v_pk_add_f32 v[146:147], v[150:151], v[146:147]
	v_mul_f32_e32 v216, v162, v162
	v_mov_b32_e32 v165, v173
	v_add_f32_e32 v150, v146, v147
	v_mul_f32_e32 v151, v220, v220
	v_mul_f32_e32 v157, v221, v221
	v_pk_add_f32 v[146:147], v[158:159], v[158:159] op_sel:[0,1] op_sel_hi:[1,0]
	v_pk_add_f32 v[152:153], v[160:161], v[160:161] op_sel:[0,1] op_sel_hi:[1,0]
	v_pk_add_f32 v[164:165], v[164:165], v[184:185]
	v_pk_add_f32 v[172:173], v[214:215], v[216:217]
	v_mov_b32_e32 v147, v151
	v_mov_b32_e32 v153, v157
	v_pk_add_f32 v[164:165], v[164:165], v[172:173]
	v_pk_add_f32 v[146:147], v[146:147], v[152:153]
	v_mul_f32_e32 v152, v183, v183
	v_mul_f32_e32 v158, v167, v167
	v_add_f32_e32 v148, v148, v149
	v_add_f32_e32 v149, v164, v165
	v_mul_f32_e32 v162, v218, v218
	v_mul_f32_e32 v164, v219, v219
	v_pk_fma_f32 v[152:153], v[182:183], v[182:183], v[152:153] op_sel_hi:[1,1,0]
	v_pk_fma_f32 v[158:159], v[166:167], v[166:167], v[158:159] op_sel_hi:[1,1,0]
	v_mov_b32_e32 v153, v162
	v_mov_b32_e32 v159, v164
	v_pk_add_f32 v[152:153], v[152:153], v[158:159]
	s_nop 0
	v_pk_add_f32 v[146:147], v[146:147], v[152:153]
	s_nop 0
	v_add_f32_e32 v151, v146, v147
	ds_bpermute_b32 v146, v187, v148
	ds_bpermute_b32 v147, v187, v149
	s_waitcnt lgkmcnt(0)
	v_pk_add_f32 v[146:147], v[148:149], v[146:147]
	ds_bpermute_b32 v148, v187, v150
	ds_bpermute_b32 v149, v187, v151
	s_waitcnt lgkmcnt(0)
	v_pk_add_f32 v[150:151], v[150:151], v[148:149]
	ds_bpermute_b32 v148, v186, v146
	ds_bpermute_b32 v149, v186, v147
	ds_bpermute_b32 v152, v186, v150
	ds_bpermute_b32 v153, v186, v151
	s_and_saveexec_b64 s[0:1], vcc
	s_cbranch_execz .LBB0_1073
	s_lshl_b32 s5, s19, 12
	s_add_i32 s5, s4, s5
	s_waitcnt lgkmcnt(0)
	v_pk_add_f32 v[150:151], v[150:151], v[152:153]
	v_pk_add_f32 v[148:149], v[146:147], v[148:149]
	v_add_u32_e32 v146, s5, v155
	ds_write_b128 v146, v[148:151]
